# v85 + SSM Y-stage MFMA blocks: both LDS fragment reads of a block issued together / 3 reads ahead in the tail (dead registers v200-209, v238-241)
# speedup vs baseline: 1.0006x; 1.0006x over previous
; #define LAS __attribute__((address_space(3)))
; __device__ __forceinline__ void mixers_phase(Frame& F, const Args& a, int l, const bool do_conv) {
;     ...
;                 __syncthreads();
;                 {
;                     f32x16 acc0 = {}, acc1 = {};
;                     const LAS unsigned char* bp0 = ux + l31 * UX_PITCH + hi * 16;
;                     const LAS unsigned char* bp1 = bp0 + 32 * UX_PITCH;
; #pragma unroll
;                     for (int ks = 0; ks < 24; ++ks) {
;                         if (ks < 16 && ks > 2 * rbk + 1) continue;
;                         const bf16x8 b0 = *(const LAS bf16x8*)(bp0 + ks * 32);
;                         const bf16x8 b1 = *(const LAS bf16x8*)(bp1 + ks * 32);
;                         acc0 = __builtin_amdgcn_mfma_f32_32x32x16_bf16(afr[ks], b0, acc0, 0, 0, 0);
;                         acc1 = __builtin_amdgcn_mfma_f32_32x32x16_bf16(afr[ks], b1, acc1, 0, 0, 0);
;                     }
.LBB0_590:
	s_and_b64 vcc, exec, s[26:27]
	s_waitcnt lgkmcnt(0)
	s_barrier
	s_cbranch_vccnz .LBB0_592
	ds_read_b128 v[200:203], v233
	ds_read_b128 v[206:209], v233 offset:25088
	s_waitcnt vmcnt(8)
	s_waitcnt lgkmcnt(1)
	v_mfma_f32_32x32x16_bf16 v[18:33], v[2:5], v[200:203], 0
	s_waitcnt lgkmcnt(0)
	v_mfma_f32_32x32x16_bf16 v[2:17], v[2:5], v[206:209], 0
	s_and_b64 vcc, exec, s[26:27]
	s_cbranch_vccz .LBB0_593
	s_branch .LBB0_594

; #define LAS __attribute__((address_space(3)))
; __device__ __forceinline__ void mixers_phase(Frame& F, const Args& a, int l, const bool do_conv) {
;     ...
;                     for (int ks = 0; ks < 24; ++ks) {
;                         if (ks < 16 && ks > 2 * rbk + 1) continue;
;                         const bf16x8 b0 = *(const LAS bf16x8*)(bp0 + ks * 32);
;                         const bf16x8 b1 = *(const LAS bf16x8*)(bp1 + ks * 32);
;                         acc0 = __builtin_amdgcn_mfma_f32_32x32x16_bf16(afr[ks], b0, acc0, 0, 0, 0);
;                         acc1 = __builtin_amdgcn_mfma_f32_32x32x16_bf16(afr[ks], b1, acc1, 0, 0, 0);
.LBB0_593:
	ds_read_b128 v[200:203], v233 offset:32
	ds_read_b128 v[206:209], v233 offset:25120
	s_waitcnt lgkmcnt(1)
	v_mfma_f32_32x32x16_bf16 v[18:33], v[54:57], v[200:203], v[18:33]
	s_waitcnt lgkmcnt(0)
	v_mfma_f32_32x32x16_bf16 v[2:17], v[54:57], v[206:209], v[2:17]
.LBB0_594:
	s_and_b64 vcc, exec, s[28:29]
	s_cbranch_vccnz .LBB0_608
	ds_read_b128 v[200:203], v233 offset:64
	ds_read_b128 v[206:209], v233 offset:25152
	s_waitcnt lgkmcnt(1)
	v_mfma_f32_32x32x16_bf16 v[18:33], v[58:61], v[200:203], v[18:33]
	s_waitcnt lgkmcnt(0)
	v_mfma_f32_32x32x16_bf16 v[2:17], v[58:61], v[206:209], v[2:17]
	s_and_b64 vcc, exec, s[30:31]
	s_cbranch_vccz .LBB0_609

; #define LAS __attribute__((address_space(3)))
; __device__ __forceinline__ void mixers_phase(Frame& F, const Args& a, int l, const bool do_conv) {
;     ...
;                     for (int ks = 0; ks < 24; ++ks) {
;                         if (ks < 16 && ks > 2 * rbk + 1) continue;
;                         const bf16x8 b0 = *(const LAS bf16x8*)(bp0 + ks * 32);
;                         const bf16x8 b1 = *(const LAS bf16x8*)(bp1 + ks * 32);
;                         acc0 = __builtin_amdgcn_mfma_f32_32x32x16_bf16(afr[ks], b0, acc0, 0, 0, 0);
;                         acc1 = __builtin_amdgcn_mfma_f32_32x32x16_bf16(afr[ks], b1, acc1, 0, 0, 0);
.LBB0_597:
	ds_read_b128 v[200:203], v233 offset:128
	ds_read_b128 v[206:209], v233 offset:25216
	s_waitcnt lgkmcnt(1)
	v_mfma_f32_32x32x16_bf16 v[18:33], v[74:77], v[200:203], v[18:33]
	s_waitcnt lgkmcnt(0)
	v_mfma_f32_32x32x16_bf16 v[2:17], v[74:77], v[206:209], v[2:17]
	s_and_b64 vcc, exec, s[50:51]
	s_cbranch_vccz .LBB0_611

; #define LAS __attribute__((address_space(3)))
; __device__ __forceinline__ void mixers_phase(Frame& F, const Args& a, int l, const bool do_conv) {
;     ...
;                     for (int ks = 0; ks < 24; ++ks) {
;                         if (ks < 16 && ks > 2 * rbk + 1) continue;
;                         const bf16x8 b0 = *(const LAS bf16x8*)(bp0 + ks * 32);
;                         const bf16x8 b1 = *(const LAS bf16x8*)(bp1 + ks * 32);
;                         acc0 = __builtin_amdgcn_mfma_f32_32x32x16_bf16(afr[ks], b0, acc0, 0, 0, 0);
;                         acc1 = __builtin_amdgcn_mfma_f32_32x32x16_bf16(afr[ks], b1, acc1, 0, 0, 0);
.LBB0_599:
	ds_read_b128 v[200:203], v233 offset:192
	ds_read_b128 v[206:209], v233 offset:25280
	s_waitcnt lgkmcnt(1)
	v_mfma_f32_32x32x16_bf16 v[18:33], v[82:85], v[200:203], v[18:33]
	s_waitcnt lgkmcnt(0)
	v_mfma_f32_32x32x16_bf16 v[2:17], v[82:85], v[206:209], v[2:17]
	s_and_b64 vcc, exec, s[52:53]
	s_cbranch_vccz .LBB0_613

; #define LAS __attribute__((address_space(3)))
; __device__ __forceinline__ void mixers_phase(Frame& F, const Args& a, int l, const bool do_conv) {
;     ...
;                     for (int ks = 0; ks < 24; ++ks) {
;                         if (ks < 16 && ks > 2 * rbk + 1) continue;
;                         const bf16x8 b0 = *(const LAS bf16x8*)(bp0 + ks * 32);
;                         const bf16x8 b1 = *(const LAS bf16x8*)(bp1 + ks * 32);
;                         acc0 = __builtin_amdgcn_mfma_f32_32x32x16_bf16(afr[ks], b0, acc0, 0, 0, 0);
;                         acc1 = __builtin_amdgcn_mfma_f32_32x32x16_bf16(afr[ks], b1, acc1, 0, 0, 0);
.LBB0_601:
	ds_read_b128 v[200:203], v233 offset:256
	ds_read_b128 v[206:209], v233 offset:25344
	s_waitcnt lgkmcnt(1)
	v_mfma_f32_32x32x16_bf16 v[18:33], v[98:101], v[200:203], v[18:33]
	s_waitcnt lgkmcnt(0)
	v_mfma_f32_32x32x16_bf16 v[2:17], v[98:101], v[206:209], v[2:17]
	s_and_b64 vcc, exec, s[56:57]
	s_cbranch_vccz .LBB0_615

; #define LAS __attribute__((address_space(3)))
; __device__ __forceinline__ void mixers_phase(Frame& F, const Args& a, int l, const bool do_conv) {
;     ...
;                     for (int ks = 0; ks < 24; ++ks) {
;                         if (ks < 16 && ks > 2 * rbk + 1) continue;
;                         const bf16x8 b0 = *(const LAS bf16x8*)(bp0 + ks * 32);
;                         const bf16x8 b1 = *(const LAS bf16x8*)(bp1 + ks * 32);
;                         acc0 = __builtin_amdgcn_mfma_f32_32x32x16_bf16(afr[ks], b0, acc0, 0, 0, 0);
;                         acc1 = __builtin_amdgcn_mfma_f32_32x32x16_bf16(afr[ks], b1, acc1, 0, 0, 0);
.LBB0_603:
	ds_read_b128 v[200:203], v233 offset:320
	ds_read_b128 v[206:209], v233 offset:25408
	s_waitcnt lgkmcnt(1)
	v_mfma_f32_32x32x16_bf16 v[18:33], v[106:109], v[200:203], v[18:33]
	s_waitcnt lgkmcnt(0)
	v_mfma_f32_32x32x16_bf16 v[2:17], v[106:109], v[206:209], v[2:17]
	s_and_b64 vcc, exec, s[60:61]
	s_cbranch_vccz .LBB0_617

; #define LAS __attribute__((address_space(3)))
; __device__ __forceinline__ void mixers_phase(Frame& F, const Args& a, int l, const bool do_conv) {
;     ...
;                     for (int ks = 0; ks < 24; ++ks) {
;                         if (ks < 16 && ks > 2 * rbk + 1) continue;
;                         const bf16x8 b0 = *(const LAS bf16x8*)(bp0 + ks * 32);
;                         const bf16x8 b1 = *(const LAS bf16x8*)(bp1 + ks * 32);
;                         acc0 = __builtin_amdgcn_mfma_f32_32x32x16_bf16(afr[ks], b0, acc0, 0, 0, 0);
;                         acc1 = __builtin_amdgcn_mfma_f32_32x32x16_bf16(afr[ks], b1, acc1, 0, 0, 0);
.LBB0_605:
	ds_read_b128 v[200:203], v233 offset:384
	ds_read_b128 v[206:209], v233 offset:25472
	s_waitcnt lgkmcnt(1)
	v_mfma_f32_32x32x16_bf16 v[18:33], v[122:125], v[200:203], v[18:33]
	s_waitcnt lgkmcnt(0)
	v_mfma_f32_32x32x16_bf16 v[2:17], v[122:125], v[206:209], v[2:17]
	s_and_b64 vcc, exec, s[64:65]
	s_cbranch_vccz .LBB0_619

; #define LAS __attribute__((address_space(3)))
; __device__ __forceinline__ void mixers_phase(Frame& F, const Args& a, int l, const bool do_conv) {
;     ...
;                     for (int ks = 0; ks < 24; ++ks) {
;                         if (ks < 16 && ks > 2 * rbk + 1) continue;
;                         const bf16x8 b0 = *(const LAS bf16x8*)(bp0 + ks * 32);
;                         const bf16x8 b1 = *(const LAS bf16x8*)(bp1 + ks * 32);
;                         acc0 = __builtin_amdgcn_mfma_f32_32x32x16_bf16(afr[ks], b0, acc0, 0, 0, 0);
;                         acc1 = __builtin_amdgcn_mfma_f32_32x32x16_bf16(afr[ks], b1, acc1, 0, 0, 0);
.LBB0_607:
	ds_read_b128 v[200:203], v233 offset:448
	ds_read_b128 v[206:209], v233 offset:25536
	s_waitcnt lgkmcnt(1)
	v_mfma_f32_32x32x16_bf16 v[18:33], v[130:133], v[200:203], v[18:33]
	s_waitcnt lgkmcnt(0)
	v_mfma_f32_32x32x16_bf16 v[2:17], v[130:133], v[206:209], v[2:17]
	s_and_b64 vcc, exec, s[68:69]
	s_cbranch_vccz .LBB0_621
	s_branch .LBB0_622

; #define LAS __attribute__((address_space(3)))
; __device__ __forceinline__ void mixers_phase(Frame& F, const Args& a, int l, const bool do_conv) {
;     ...
;                     for (int ks = 0; ks < 24; ++ks) {
;                         if (ks < 16 && ks > 2 * rbk + 1) continue;
;                         const bf16x8 b0 = *(const LAS bf16x8*)(bp0 + ks * 32);
;                         const bf16x8 b1 = *(const LAS bf16x8*)(bp1 + ks * 32);
;                         acc0 = __builtin_amdgcn_mfma_f32_32x32x16_bf16(afr[ks], b0, acc0, 0, 0, 0);
;                         acc1 = __builtin_amdgcn_mfma_f32_32x32x16_bf16(afr[ks], b1, acc1, 0, 0, 0);
.LBB0_609:
	ds_read_b128 v[200:203], v233 offset:96
	ds_read_b128 v[206:209], v233 offset:25184
	s_waitcnt lgkmcnt(1)
	v_mfma_f32_32x32x16_bf16 v[18:33], v[66:69], v[200:203], v[18:33]
	s_waitcnt lgkmcnt(0)
	v_mfma_f32_32x32x16_bf16 v[2:17], v[66:69], v[206:209], v[2:17]
	s_and_b64 vcc, exec, s[34:35]
	s_cbranch_vccz .LBB0_597

; #define LAS __attribute__((address_space(3)))
; __device__ __forceinline__ void mixers_phase(Frame& F, const Args& a, int l, const bool do_conv) {
;     ...
;                     for (int ks = 0; ks < 24; ++ks) {
;                         if (ks < 16 && ks > 2 * rbk + 1) continue;
;                         const bf16x8 b0 = *(const LAS bf16x8*)(bp0 + ks * 32);
;                         const bf16x8 b1 = *(const LAS bf16x8*)(bp1 + ks * 32);
;                         acc0 = __builtin_amdgcn_mfma_f32_32x32x16_bf16(afr[ks], b0, acc0, 0, 0, 0);
;                         acc1 = __builtin_amdgcn_mfma_f32_32x32x16_bf16(afr[ks], b1, acc1, 0, 0, 0);
.LBB0_611:
	ds_read_b128 v[200:203], v233 offset:160
	ds_read_b128 v[206:209], v233 offset:25248
	s_waitcnt lgkmcnt(1)
	v_mfma_f32_32x32x16_bf16 v[18:33], v[78:81], v[200:203], v[18:33]
	s_waitcnt lgkmcnt(0)
	v_mfma_f32_32x32x16_bf16 v[2:17], v[78:81], v[206:209], v[2:17]
	s_and_b64 vcc, exec, s[2:3]
	s_cbranch_vccz .LBB0_599

; #define LAS __attribute__((address_space(3)))
; __device__ __forceinline__ void mixers_phase(Frame& F, const Args& a, int l, const bool do_conv) {
;     ...
;                     for (int ks = 0; ks < 24; ++ks) {
;                         if (ks < 16 && ks > 2 * rbk + 1) continue;
;                         const bf16x8 b0 = *(const LAS bf16x8*)(bp0 + ks * 32);
;                         const bf16x8 b1 = *(const LAS bf16x8*)(bp1 + ks * 32);
;                         acc0 = __builtin_amdgcn_mfma_f32_32x32x16_bf16(afr[ks], b0, acc0, 0, 0, 0);
;                         acc1 = __builtin_amdgcn_mfma_f32_32x32x16_bf16(afr[ks], b1, acc1, 0, 0, 0);
.LBB0_613:
	ds_read_b128 v[200:203], v233 offset:224
	ds_read_b128 v[206:209], v233 offset:25312
	s_waitcnt lgkmcnt(1)
	v_mfma_f32_32x32x16_bf16 v[18:33], v[90:93], v[200:203], v[18:33]
	s_waitcnt lgkmcnt(0)
	v_mfma_f32_32x32x16_bf16 v[2:17], v[90:93], v[206:209], v[2:17]
	s_and_b64 vcc, exec, s[54:55]
	s_cbranch_vccz .LBB0_601

; #define LAS __attribute__((address_space(3)))
; __device__ __forceinline__ void mixers_phase(Frame& F, const Args& a, int l, const bool do_conv) {
;     ...
;                     for (int ks = 0; ks < 24; ++ks) {
;                         if (ks < 16 && ks > 2 * rbk + 1) continue;
;                         const bf16x8 b0 = *(const LAS bf16x8*)(bp0 + ks * 32);
;                         const bf16x8 b1 = *(const LAS bf16x8*)(bp1 + ks * 32);
;                         acc0 = __builtin_amdgcn_mfma_f32_32x32x16_bf16(afr[ks], b0, acc0, 0, 0, 0);
;                         acc1 = __builtin_amdgcn_mfma_f32_32x32x16_bf16(afr[ks], b1, acc1, 0, 0, 0);
.LBB0_615:
	ds_read_b128 v[200:203], v233 offset:288
	ds_read_b128 v[206:209], v233 offset:25376
	s_waitcnt lgkmcnt(1)
	v_mfma_f32_32x32x16_bf16 v[18:33], v[102:105], v[200:203], v[18:33]
	s_waitcnt lgkmcnt(0)
	v_mfma_f32_32x32x16_bf16 v[2:17], v[102:105], v[206:209], v[2:17]
	s_and_b64 vcc, exec, s[58:59]
	s_cbranch_vccz .LBB0_603

; #define LAS __attribute__((address_space(3)))
; __device__ __forceinline__ void mixers_phase(Frame& F, const Args& a, int l, const bool do_conv) {
;     ...
;                     for (int ks = 0; ks < 24; ++ks) {
;                         if (ks < 16 && ks > 2 * rbk + 1) continue;
;                         const bf16x8 b0 = *(const LAS bf16x8*)(bp0 + ks * 32);
;                         const bf16x8 b1 = *(const LAS bf16x8*)(bp1 + ks * 32);
;                         acc0 = __builtin_amdgcn_mfma_f32_32x32x16_bf16(afr[ks], b0, acc0, 0, 0, 0);
;                         acc1 = __builtin_amdgcn_mfma_f32_32x32x16_bf16(afr[ks], b1, acc1, 0, 0, 0);
.LBB0_617:
	ds_read_b128 v[200:203], v233 offset:352
	ds_read_b128 v[206:209], v233 offset:25440
	s_waitcnt lgkmcnt(1)
	v_mfma_f32_32x32x16_bf16 v[18:33], v[114:117], v[200:203], v[18:33]
	s_waitcnt lgkmcnt(0)
	v_mfma_f32_32x32x16_bf16 v[2:17], v[114:117], v[206:209], v[2:17]
	s_and_b64 vcc, exec, s[62:63]
	s_cbranch_vccz .LBB0_605

; #define LAS __attribute__((address_space(3)))
; __device__ __forceinline__ void mixers_phase(Frame& F, const Args& a, int l, const bool do_conv) {
;     ...
;                     for (int ks = 0; ks < 24; ++ks) {
;                         if (ks < 16 && ks > 2 * rbk + 1) continue;
;                         const bf16x8 b0 = *(const LAS bf16x8*)(bp0 + ks * 32);
;                         const bf16x8 b1 = *(const LAS bf16x8*)(bp1 + ks * 32);
;                         acc0 = __builtin_amdgcn_mfma_f32_32x32x16_bf16(afr[ks], b0, acc0, 0, 0, 0);
;                         acc1 = __builtin_amdgcn_mfma_f32_32x32x16_bf16(afr[ks], b1, acc1, 0, 0, 0);
.LBB0_619:
	ds_read_b128 v[200:203], v233 offset:416
	ds_read_b128 v[206:209], v233 offset:25504
	s_waitcnt lgkmcnt(1)
	v_mfma_f32_32x32x16_bf16 v[18:33], v[126:129], v[200:203], v[18:33]
	s_waitcnt lgkmcnt(0)
	v_mfma_f32_32x32x16_bf16 v[2:17], v[126:129], v[206:209], v[2:17]
	s_and_b64 vcc, exec, s[66:67]
	s_cbranch_vccz .LBB0_607

; #define LAS __attribute__((address_space(3)))
; __device__ __forceinline__ unsigned pk2(float lo, float hi) { const f32x2 v = {lo, hi}; const bf16x2_hw b = __builtin_convertvector(v, bf16x2_hw); return __builtin_bit_cast(unsigned, b); }
; __device__ __forceinline__ float gelu_tanh(float y) { const float t = (1.5957691216057308f * LOG2E) * (y + 0.044715f * y * y * y); return y * __builtin_amdgcn_rcpf(1.0f + __builtin_amdgcn_exp2f(-t)); }
; __device__ __forceinline__ void mixers_phase(Frame& F, const Args& a, int l, const bool do_conv) {
;     ...
;                 {
;                     f32x16 acc0 = {}, acc1 = {};
;                     const LAS unsigned char* bp0 = ux + l31 * UX_PITCH + hi * 16;
;                     const LAS unsigned char* bp1 = bp0 + 32 * UX_PITCH;
; #pragma unroll
;                     for (int ks = 0; ks < 24; ++ks) {
;                         if (ks < 16 && ks > 2 * rbk + 1) continue;
;                         const bf16x8 b0 = *(const LAS bf16x8*)(bp0 + ks * 32);
;                         const bf16x8 b1 = *(const LAS bf16x8*)(bp1 + ks * 32);
;                         acc0 = __builtin_amdgcn_mfma_f32_32x32x16_bf16(afr[ks], b0, acc0, 0, 0, 0);
;                         acc1 = __builtin_amdgcn_mfma_f32_32x32x16_bf16(afr[ks], b1, acc1, 0, 0, 0);
;                     }
; #pragma unroll
;                     for (int cbk = 0; cbk < 2; ++cbk) {
;                         unsigned wx[4], wy[4];
; #pragma unroll
;                         for (int q = 0; q < 4; ++q) {
;                             float y0, y1, y2, y3;
;                             if (cbk == 0) { y0 = acc0[4 * q]; y1 = acc0[4 * q + 1]; y2 = acc0[4 * q + 2]; y3 = acc0[4 * q + 3]; } else { y0 = acc1[4 * q]; y1 = acc1[4 * q + 1]; y2 = acc1[4 * q + 2]; y3 = acc1[4 * q + 3]; }
;                             wx[q] = pk2(gelu_tanh(y0), gelu_tanh(y1)); wy[q] = pk2(gelu_tanh(y2), gelu_tanh(y3));
.LBB0_621:
	ds_read_b128 v[200:203], v233 offset:480
	ds_read_b128 v[206:209], v233 offset:25568
	s_waitcnt lgkmcnt(1)
	v_mfma_f32_32x32x16_bf16 v[18:33], v[138:141], v[200:203], v[18:33]
	s_waitcnt lgkmcnt(0)
	v_mfma_f32_32x32x16_bf16 v[2:17], v[138:141], v[206:209], v[2:17]
.LBB0_622:
	ds_read_b128 v[200:203], v233 offset:25600
	ds_read_b128 v[206:209], v233 offset:512
	ds_read_b128 v[238:241], v233 offset:544
	v_or_b32_e32 v0, s14, v199
	v_readlane_b32 s2, v254, 18
	s_waitcnt vmcnt(7)
	s_waitcnt lgkmcnt(2)
	v_mfma_f32_32x32x16_bf16 v[2:17], v[134:137], v[200:203], v[2:17]
	ds_read_b128 v[200:203], v233 offset:25632
	s_add_i32 s2, s13, s2
	s_mov_b32 s68, s47
	s_min_i32 s13, s2, s10
	s_movk_i32 s14, 0x400
	s_mov_b64 s[2:3], 0
	s_and_b64 vcc, exec, s[6:7]
	s_waitcnt lgkmcnt(2)
	v_mfma_f32_32x32x16_bf16 v[18:33], v[134:137], v[206:209], v[18:33]
	s_waitcnt vmcnt(6)
	ds_read_b128 v[206:209], v233 offset:576
	s_waitcnt lgkmcnt(2)
	v_mfma_f32_32x32x16_bf16 v[18:33], v[118:121], v[238:241], v[18:33]
	ds_read_b128 v[238:241], v233 offset:25664
	s_waitcnt lgkmcnt(2)
	v_mfma_f32_32x32x16_bf16 v[2:17], v[118:121], v[200:203], v[2:17]
	s_waitcnt vmcnt(5)
	ds_read_b128 v[200:203], v233 offset:608
	s_waitcnt lgkmcnt(2)
	v_mfma_f32_32x32x16_bf16 v[18:33], v[110:113], v[206:209], v[18:33]
	ds_read_b128 v[206:209], v233 offset:25696
	s_waitcnt lgkmcnt(2)
	v_mfma_f32_32x32x16_bf16 v[2:17], v[110:113], v[238:241], v[2:17]
	s_waitcnt vmcnt(4)
	ds_read_b128 v[238:241], v233 offset:640
	s_waitcnt lgkmcnt(2)
	v_mfma_f32_32x32x16_bf16 v[18:33], v[94:97], v[200:203], v[18:33]
	ds_read_b128 v[200:203], v233 offset:25728
	s_waitcnt lgkmcnt(2)
	v_mfma_f32_32x32x16_bf16 v[2:17], v[94:97], v[206:209], v[2:17]
	s_waitcnt vmcnt(3)
	ds_read_b128 v[206:209], v233 offset:672
	s_waitcnt lgkmcnt(2)
	v_mfma_f32_32x32x16_bf16 v[18:33], v[86:89], v[238:241], v[18:33]
	ds_read_b128 v[238:241], v233 offset:25760
	s_waitcnt lgkmcnt(2)
	v_mfma_f32_32x32x16_bf16 v[2:17], v[86:89], v[200:203], v[2:17]
	s_waitcnt vmcnt(2)
	ds_read_b128 v[200:203], v233 offset:704
	s_waitcnt lgkmcnt(2)
	v_mfma_f32_32x32x16_bf16 v[18:33], v[70:73], v[206:209], v[18:33]
	ds_read_b128 v[206:209], v233 offset:25792
	s_waitcnt lgkmcnt(2)
	v_mfma_f32_32x32x16_bf16 v[2:17], v[70:73], v[238:241], v[2:17]
	s_waitcnt vmcnt(1)
	ds_read_b128 v[238:241], v233 offset:736
	s_waitcnt lgkmcnt(2)
	v_mfma_f32_32x32x16_bf16 v[18:33], v[62:65], v[200:203], v[18:33]
	ds_read_b128 v[200:203], v233 offset:25824
	s_waitcnt lgkmcnt(2)
	v_mfma_f32_32x32x16_bf16 v[2:17], v[62:65], v[206:209], v[2:17]
	s_waitcnt vmcnt(0)
	s_waitcnt lgkmcnt(1)
	v_mfma_f32_32x32x16_bf16 v[18:33], v[50:53], v[238:241], v[18:33]
	s_waitcnt lgkmcnt(0)
	v_mfma_f32_32x32x16_bf16 v[2:17], v[50:53], v[200:203], v[2:17]
	s_nop 9
	v_mul_f32_e32 v50, 0x3d372713, v18
	v_mul_f32_e32 v51, 0x3d372713, v19
	v_mul_f32_e32 v50, v18, v50
	v_mul_f32_e32 v51, v19, v51
	v_fma_f32 v50, v18, v50, v18
	v_fma_f32 v51, v19, v51, v19
	v_mul_f32_e32 v50, 0xc0135761, v50
	v_mul_f32_e32 v51, 0xc0135761, v51
	v_exp_f32_e32 v50, v50
	v_exp_f32_e32 v51, v51
	v_add_f32_e32 v50, 1.0, v50
	v_add_f32_e32 v51, 1.0, v51
	v_rcp_f32_e32 v50, v50
	v_rcp_f32_e32 v51, v51
	s_nop 0
	v_pk_mul_f32 v[18:19], v[18:19], v[50:51]
	s_nop 0
	v_cvt_pk_bf16_f32 v18, v18, v19
	v_mul_f32_e32 v19, 0x3d372713, v20
	v_mul_f32_e32 v19, v20, v19
	v_fma_f32 v19, v20, v19, v20
	v_mul_f32_e32 v19, 0xc0135761, v19
	v_exp_f32_e32 v19, v19
	s_nop 0
	v_add_f32_e32 v19, 1.0, v19
	v_rcp_f32_e32 v50, v19
	v_mul_f32_e32 v19, 0x3d372713, v21
	v_mul_f32_e32 v19, v21, v19
	v_fma_f32 v19, v21, v19, v21
	v_mul_f32_e32 v19, 0xc0135761, v19
	v_exp_f32_e32 v19, v19
	s_nop 0
	v_add_f32_e32 v19, 1.0, v19
	v_rcp_f32_e32 v51, v19
	s_nop 0
	v_pk_mul_f32 v[20:21], v[20:21], v[50:51]
	s_nop 0
	v_cvt_pk_bf16_f32 v19, v20, v21
	v_mul_f32_e32 v20, 0x3d372713, v22
	v_mul_f32_e32 v21, 0x3d372713, v23
	v_mul_f32_e32 v20, v22, v20
	v_mul_f32_e32 v21, v23, v21
	v_fma_f32 v20, v22, v20, v22
	v_fma_f32 v21, v23, v21, v23
	v_mul_f32_e32 v20, 0xc0135761, v20
	v_mul_f32_e32 v21, 0xc0135761, v21
	v_exp_f32_e32 v20, v20
	v_exp_f32_e32 v21, v21
	v_add_f32_e32 v20, 1.0, v20
	v_add_f32_e32 v21, 1.0, v21
	v_rcp_f32_e32 v20, v20
	v_rcp_f32_e32 v21, v21
	s_nop 0
	v_pk_mul_f32 v[20:21], v[22:23], v[20:21]
	s_nop 0
	v_cvt_pk_bf16_f32 v22, v20, v21
	v_mul_f32_e32 v20, 0x3d372713, v24
	v_mul_f32_e32 v21, 0x3d372713, v25
	v_mul_f32_e32 v20, v24, v20
	v_mul_f32_e32 v21, v25, v21
	v_fma_f32 v20, v24, v20, v24
	v_fma_f32 v21, v25, v21, v25
	v_mul_f32_e32 v20, 0xc0135761, v20
	v_mul_f32_e32 v21, 0xc0135761, v21
	v_exp_f32_e32 v20, v20
	v_exp_f32_e32 v21, v21
	v_add_f32_e32 v20, 1.0, v20
	v_add_f32_e32 v21, 1.0, v21
	v_rcp_f32_e32 v20, v20
	v_rcp_f32_e32 v21, v21
	s_nop 0
	v_pk_mul_f32 v[20:21], v[24:25], v[20:21]
	s_nop 0
	v_cvt_pk_bf16_f32 v23, v20, v21
	v_mul_f32_e32 v20, 0x3d372713, v26
	v_mul_f32_e32 v21, 0x3d372713, v27
	v_mul_f32_e32 v20, v26, v20
	v_mul_f32_e32 v21, v27, v21
	v_fma_f32 v20, v26, v20, v26
	v_fma_f32 v21, v27, v21, v27
	v_mul_f32_e32 v20, 0xc0135761, v20
	v_mul_f32_e32 v21, 0xc0135761, v21
	v_exp_f32_e32 v20, v20
	v_exp_f32_e32 v21, v21
	v_add_f32_e32 v20, 1.0, v20
	v_add_f32_e32 v21, 1.0, v21
	v_rcp_f32_e32 v20, v20
	v_rcp_f32_e32 v21, v21
	s_nop 0
	v_pk_mul_f32 v[20:21], v[26:27], v[20:21]
	s_nop 0
	v_cvt_pk_bf16_f32 v20, v20, v21
	v_mul_f32_e32 v21, 0x3d372713, v28
	v_mul_f32_e32 v21, v28, v21
	v_fma_f32 v21, v28, v21, v28
	v_mul_f32_e32 v21, 0xc0135761, v21
	v_exp_f32_e32 v21, v21
	v_permlane32_swap_b32_e32 v18, v20
	v_add_f32_e32 v21, 1.0, v21
	v_rcp_f32_e32 v24, v21
	v_mul_f32_e32 v21, 0x3d372713, v29
	v_mul_f32_e32 v21, v29, v21
; __device__ __forceinline__ unsigned pk2(float lo, float hi) { const f32x2 v = {lo, hi}; const bf16x2_hw b = __builtin_convertvector(v, bf16x2_hw); return __builtin_bit_cast(unsigned, b); }
; __device__ __forceinline__ float gelu_tanh(float y) { const float t = (1.5957691216057308f * LOG2E) * (y + 0.044715f * y * y * y); return y * __builtin_amdgcn_rcpf(1.0f + __builtin_amdgcn_exp2f(-t)); }
; __device__ __forceinline__ void mixers_phase(Frame& F, const Args& a, int l, const bool do_conv) {
;     ...
; #pragma unroll
;                     for (int cbk = 0; cbk < 2; ++cbk) {
;                         unsigned wx[4], wy[4];
; #pragma unroll
;                         for (int q = 0; q < 4; ++q) {
;                             float y0, y1, y2, y3;
;                             if (cbk == 0) { y0 = acc0[4 * q]; y1 = acc0[4 * q + 1]; y2 = acc0[4 * q + 2]; y3 = acc0[4 * q + 3]; } else { y0 = acc1[4 * q]; y1 = acc1[4 * q + 1]; y2 = acc1[4 * q + 2]; y3 = acc1[4 * q + 3]; }
;                             wx[q] = pk2(gelu_tanh(y0), gelu_tanh(y1)); wy[q] = pk2(gelu_tanh(y2), gelu_tanh(y3));
;                         }
;                         const auto s0x = __builtin_amdgcn_permlane32_swap(wx[0], wx[2], false, false), s0y = __builtin_amdgcn_permlane32_swap(wy[0], wy[2], false, false);
;                         const auto s1x = __builtin_amdgcn_permlane32_swap(wx[1], wx[3], false, false), s1y = __builtin_amdgcn_permlane32_swap(wy[1], wy[3], false, false);
;                         u32x4 lo4, hi4; lo4.x = s0x[0]; lo4.y = s0y[0]; lo4.z = s0x[1]; lo4.w = s0y[1]; hi4.x = s1x[0]; hi4.y = s1y[0]; hi4.z = s1x[1]; hi4.w = s1y[1];
;                         const size_t row = (size_t)b * SEQ + half * 1024 + 16 * (cbk * 32 + l31) + 2 * rbk + hi;
;                         *(u32x4*)(YS + row * 512 + g * 16) = lo4; *(u32x4*)(YS + row * 512 + g * 16 + 8) = hi4;
;                     }
;                 }
;                 __syncthreads();
	v_fma_f32 v21, v29, v21, v29
	v_mul_f32_e32 v21, 0xc0135761, v21
	v_exp_f32_e32 v21, v21
	s_nop 0
	v_add_f32_e32 v21, 1.0, v21
	v_rcp_f32_e32 v25, v21
	s_nop 0
	v_pk_mul_f32 v[24:25], v[28:29], v[24:25]
	s_nop 0
	v_cvt_pk_bf16_f32 v21, v24, v25
	v_mul_f32_e32 v24, 0x3d372713, v30
	v_mul_f32_e32 v25, 0x3d372713, v31
	v_mul_f32_e32 v24, v30, v24
	v_mul_f32_e32 v25, v31, v25
	v_fma_f32 v24, v30, v24, v30
	v_fma_f32 v25, v31, v25, v31
	v_mul_f32_e32 v24, 0xc0135761, v24
	v_mul_f32_e32 v25, 0xc0135761, v25
	v_exp_f32_e32 v24, v24
	v_exp_f32_e32 v25, v25
	v_permlane32_swap_b32_e32 v19, v21
	v_add_f32_e32 v24, 1.0, v24
	v_add_f32_e32 v25, 1.0, v25
	v_rcp_f32_e32 v24, v24
	v_rcp_f32_e32 v25, v25
	s_nop 0
	v_pk_mul_f32 v[24:25], v[30:31], v[24:25]
	s_nop 0
	v_cvt_pk_bf16_f32 v24, v24, v25
	v_mul_f32_e32 v25, 0x3d372713, v32
	v_mul_f32_e32 v25, v32, v25
	v_fma_f32 v25, v32, v25, v32
	v_mul_f32_e32 v25, 0xc0135761, v25
	v_exp_f32_e32 v25, v25
	v_permlane32_swap_b32_e32 v22, v24
	v_add_f32_e32 v25, 1.0, v25
	v_rcp_f32_e32 v26, v25
	v_mul_f32_e32 v25, 0x3d372713, v33
	v_mul_f32_e32 v25, v33, v25
	v_fma_f32 v25, v33, v25, v33
	v_mul_f32_e32 v25, 0xc0135761, v25
	v_exp_f32_e32 v25, v25
	s_nop 0
	v_add_f32_e32 v25, 1.0, v25
	v_rcp_f32_e32 v27, v25
	s_nop 0
	v_pk_mul_f32 v[26:27], v[32:33], v[26:27]
	s_nop 0
	v_cvt_pk_bf16_f32 v25, v26, v27
	v_lshl_add_u64 v[26:27], v[150:151], 0, v[0:1]
	v_lshlrev_b64 v[26:27], 10, v[26:27]
	v_lshl_add_u64 v[26:27], s[0:1], 0, v[26:27]
	v_permlane32_swap_b32_e32 v23, v25
	global_store_dwordx4 v[26:27], v[18:21], off
	global_store_dwordx4 v[26:27], v[22:25], off offset:16
	v_or_b32_e32 v0, 0x200, v0
	v_mul_f32_e32 v18, 0x3d372713, v2
	v_mul_f32_e32 v19, 0x3d372713, v3
	v_mul_f32_e32 v18, v2, v18
	v_mul_f32_e32 v19, v3, v19
	v_fma_f32 v18, v2, v18, v2
	v_fma_f32 v19, v3, v19, v3
	v_mul_f32_e32 v18, 0xc0135761, v18
	v_mul_f32_e32 v19, 0xc0135761, v19
	v_exp_f32_e32 v18, v18
	v_exp_f32_e32 v19, v19
	v_add_f32_e32 v18, 1.0, v18
	v_add_f32_e32 v19, 1.0, v19
	v_rcp_f32_e32 v18, v18
	v_rcp_f32_e32 v19, v19
	s_nop 0
	v_pk_mul_f32 v[2:3], v[2:3], v[18:19]
	s_nop 0
	v_cvt_pk_bf16_f32 v2, v2, v3
	v_mul_f32_e32 v3, 0x3d372713, v4
	v_mul_f32_e32 v3, v4, v3
	v_fma_f32 v3, v4, v3, v4
	v_mul_f32_e32 v3, 0xc0135761, v3
	v_exp_f32_e32 v3, v3
	s_nop 0
	v_add_f32_e32 v3, 1.0, v3
	v_rcp_f32_e32 v18, v3
	v_mul_f32_e32 v3, 0x3d372713, v5
	v_mul_f32_e32 v3, v5, v3
	v_fma_f32 v3, v5, v3, v5
	v_mul_f32_e32 v3, 0xc0135761, v3
	v_exp_f32_e32 v3, v3
	s_nop 0
	v_add_f32_e32 v3, 1.0, v3
	v_rcp_f32_e32 v19, v3
	s_nop 0
	v_pk_mul_f32 v[4:5], v[4:5], v[18:19]
	s_nop 0
	v_cvt_pk_bf16_f32 v3, v4, v5
	v_mul_f32_e32 v4, 0x3d372713, v6
	v_mul_f32_e32 v5, 0x3d372713, v7
	v_mul_f32_e32 v4, v6, v4
	v_mul_f32_e32 v5, v7, v5
	v_fma_f32 v4, v6, v4, v6
	v_fma_f32 v5, v7, v5, v7
	v_mul_f32_e32 v4, 0xc0135761, v4
	v_mul_f32_e32 v5, 0xc0135761, v5
	v_exp_f32_e32 v4, v4
	v_exp_f32_e32 v5, v5
	v_add_f32_e32 v4, 1.0, v4
	v_add_f32_e32 v5, 1.0, v5
	v_rcp_f32_e32 v4, v4
	v_rcp_f32_e32 v5, v5
	s_nop 0
	v_pk_mul_f32 v[4:5], v[6:7], v[4:5]
	s_nop 0
	v_cvt_pk_bf16_f32 v6, v4, v5
	v_mul_f32_e32 v4, 0x3d372713, v8
	v_mul_f32_e32 v5, 0x3d372713, v9
	v_mul_f32_e32 v4, v8, v4
	v_mul_f32_e32 v5, v9, v5
	v_fma_f32 v4, v8, v4, v8
	v_fma_f32 v5, v9, v5, v9
	v_mul_f32_e32 v4, 0xc0135761, v4
	v_mul_f32_e32 v5, 0xc0135761, v5
	v_exp_f32_e32 v4, v4
	v_exp_f32_e32 v5, v5
	v_add_f32_e32 v4, 1.0, v4
	v_add_f32_e32 v5, 1.0, v5
	v_rcp_f32_e32 v4, v4
	v_rcp_f32_e32 v5, v5
	s_nop 0
	v_pk_mul_f32 v[4:5], v[8:9], v[4:5]
	s_nop 0
	v_cvt_pk_bf16_f32 v7, v4, v5
	v_mul_f32_e32 v4, 0x3d372713, v10
	v_mul_f32_e32 v5, 0x3d372713, v11
	v_mul_f32_e32 v4, v10, v4
	v_mul_f32_e32 v5, v11, v5
	v_fma_f32 v4, v10, v4, v10
	v_fma_f32 v5, v11, v5, v11
	v_mul_f32_e32 v4, 0xc0135761, v4
	v_mul_f32_e32 v5, 0xc0135761, v5
	v_exp_f32_e32 v4, v4
	v_exp_f32_e32 v5, v5
	v_add_f32_e32 v4, 1.0, v4
	v_add_f32_e32 v5, 1.0, v5
	v_rcp_f32_e32 v4, v4
	v_rcp_f32_e32 v5, v5
	s_nop 0
	v_pk_mul_f32 v[4:5], v[10:11], v[4:5]
	s_nop 0
	v_cvt_pk_bf16_f32 v4, v4, v5
	v_mul_f32_e32 v5, 0x3d372713, v12
	v_mul_f32_e32 v5, v12, v5
	v_fma_f32 v5, v12, v5, v12
	v_mul_f32_e32 v5, 0xc0135761, v5
	v_exp_f32_e32 v5, v5
	v_permlane32_swap_b32_e32 v2, v4
	v_add_f32_e32 v5, 1.0, v5
	v_rcp_f32_e32 v8, v5
	v_mul_f32_e32 v5, 0x3d372713, v13
	v_mul_f32_e32 v5, v13, v5
	v_fma_f32 v5, v13, v5, v13
	v_mul_f32_e32 v5, 0xc0135761, v5
	v_exp_f32_e32 v5, v5
	s_nop 0
	v_add_f32_e32 v5, 1.0, v5
	v_rcp_f32_e32 v9, v5
	s_nop 0
	v_pk_mul_f32 v[8:9], v[12:13], v[8:9]
	s_nop 0
	v_cvt_pk_bf16_f32 v5, v8, v9
	v_mul_f32_e32 v8, 0x3d372713, v14
	v_mul_f32_e32 v9, 0x3d372713, v15
	v_mul_f32_e32 v8, v14, v8
	v_mul_f32_e32 v9, v15, v9
	v_fma_f32 v8, v14, v8, v14
	v_fma_f32 v9, v15, v9, v15
	v_mul_f32_e32 v8, 0xc0135761, v8
	v_mul_f32_e32 v9, 0xc0135761, v9
	v_exp_f32_e32 v8, v8
	v_exp_f32_e32 v9, v9
	v_permlane32_swap_b32_e32 v3, v5
	v_add_f32_e32 v8, 1.0, v8
	v_add_f32_e32 v9, 1.0, v9
	v_rcp_f32_e32 v8, v8
	v_rcp_f32_e32 v9, v9
	s_nop 0
	v_pk_mul_f32 v[8:9], v[14:15], v[8:9]
	s_nop 0
	v_cvt_pk_bf16_f32 v8, v8, v9
	v_mul_f32_e32 v9, 0x3d372713, v16
	v_mul_f32_e32 v9, v16, v9
	v_fma_f32 v9, v16, v9, v16
	v_mul_f32_e32 v9, 0xc0135761, v9
	v_exp_f32_e32 v9, v9
	v_permlane32_swap_b32_e32 v6, v8
	v_add_f32_e32 v9, 1.0, v9
	v_rcp_f32_e32 v10, v9
	v_mul_f32_e32 v9, 0x3d372713, v17
	v_mul_f32_e32 v9, v17, v9
	v_fma_f32 v9, v17, v9, v17
	v_mul_f32_e32 v9, 0xc0135761, v9
	v_exp_f32_e32 v9, v9
	s_nop 0
	v_add_f32_e32 v9, 1.0, v9
	v_rcp_f32_e32 v11, v9
	s_nop 0
	v_pk_mul_f32 v[10:11], v[16:17], v[10:11]
	s_nop 0
	v_cvt_pk_bf16_f32 v9, v10, v11
	v_lshl_add_u64 v[10:11], v[150:151], 0, v[0:1]
	v_lshlrev_b64 v[10:11], 10, v[10:11]
	v_lshl_add_u64 v[10:11], s[0:1], 0, v[10:11]
	v_permlane32_swap_b32_e32 v7, v9
	global_store_dwordx4 v[10:11], v[2:5], off
	global_store_dwordx4 v[10:11], v[6:9], off offset:16
	s_barrier
	s_cbranch_vccnz .LBB0_524
	v_mov_b32_e32 v172, v174
	v_mov_b32_e32 v173, v175
	s_branch .LBB0_532

; template <class Epi, bool ALIGN_EPI, bool SP2, class Hook>
; __device__ __forceinline__ void gemm_phase(LAS unsigned char* lds, const Gemm g, const StaticOrder& S, const Epi& E, Acc& acc, const bool fresh, const Hook& H, const int wave_id) {
;     ...
;             const Src a1 = cA + (size_t)(t + 1) * kstep;
;             const Src a2 = last ? nA : cA + (size_t)(t + 2) * kstep, b2 = last ? nB : cB + (size_t)(t + 2) * kstep;
;             const Src a3 = a2 + kstep, b3 = b2 + kstep;
.LBB0_702:
	v_add_u32_e32 v70, 0x10000, v216
	v_add_u32_e32 v118, 0x14000, v216
	ds_read_b128 v[34:37], v70
	ds_read_b128 v[46:49], v70 offset:1024
	ds_read_b128 v[58:61], v70 offset:2048
	ds_read_b128 v[70:73], v70 offset:3072
	ds_read_b128 v[82:85], v118
	ds_read_b128 v[94:97], v118 offset:1024
	ds_read_b128 v[106:109], v118 offset:2048
	ds_read_b128 v[118:121], v118 offset:3072
	s_add_i32 s12, s55, 0xfffe0080
	s_cmp_eq_u32 s57, 4
	s_cselect_b32 s60, s53, s12
	s_cselect_b32 s13, s29, s77
	s_cselect_b32 s12, s28, s76
	s_cselect_b32 s15, s31, s35
	s_cselect_b32 s14, s30, s34
	s_cselect_b32 s58, s54, s56
	s_cselect_b32 s16, s2, s8
	s_cselect_b32 s17, s3, s9
	s_cselect_b32 s18, s26, s10
	s_cselect_b32 s19, s27, s11
	s_or_b32 s59, s60, 0x80
	s_mov_b32 m0, s45
	s_waitcnt vmcnt(14)
	ds_read_b128 v[130:133], v217
	ds_read_b128 v[142:145], v217 offset:1024
	ds_read_b128 v[154:157], v217 offset:2048
	ds_read_b128 v[166:169], v217 offset:3072
	ds_read_b128 v[174:177], v217 offset:4096
	ds_read_b128 v[182:185], v217 offset:5120
	ds_read_b128 v[186:189], v217 offset:6144
	ds_read_b128 v[190:193], v217 offset:7168
	buffer_load_dwordx4 v0, s[8:11], s55 offen lds
	s_mov_b32 m0, s46
	s_nop 0
	buffer_load_dwordx4 v214, s[8:11], s55 offen lds
	s_waitcnt vmcnt(8)
	s_waitcnt lgkmcnt(0)
	s_setprio 1
	s_barrier
	v_mfma_f32_16x16x32_bf16 v[178:181], v[34:37], v[130:133], v[178:181]
	v_mfma_f32_16x16x32_bf16 v[170:173], v[58:61], v[130:133], v[170:173]
	v_mfma_f32_16x16x32_bf16 v[150:153], v[34:37], v[154:157], v[150:153]
	v_mfma_f32_16x16x32_bf16 v[146:149], v[58:61], v[154:157], v[146:149]
	v_mfma_f32_16x16x32_bf16 v[126:129], v[34:37], v[174:177], v[126:129]
	v_mfma_f32_16x16x32_bf16 v[122:125], v[58:61], v[174:177], v[122:125]
	v_mfma_f32_16x16x32_bf16 v[102:105], v[34:37], v[186:189], v[102:105]
	v_mfma_f32_16x16x32_bf16 v[98:101], v[58:61], v[186:189], v[98:101]
	v_mfma_f32_16x16x32_bf16 v[178:181], v[46:49], v[142:145], v[178:181]
	v_mfma_f32_16x16x32_bf16 v[170:173], v[70:73], v[142:145], v[170:173]
	v_mfma_f32_16x16x32_bf16 v[150:153], v[46:49], v[166:169], v[150:153]
	v_mfma_f32_16x16x32_bf16 v[146:149], v[70:73], v[166:169], v[146:149]
	v_mfma_f32_16x16x32_bf16 v[126:129], v[46:49], v[182:185], v[126:129]
	v_mfma_f32_16x16x32_bf16 v[122:125], v[70:73], v[182:185], v[122:125]
	v_mfma_f32_16x16x32_bf16 v[102:105], v[46:49], v[190:193], v[102:105]
	v_mfma_f32_16x16x32_bf16 v[98:101], v[70:73], v[190:193], v[98:101]
	v_mfma_f32_16x16x32_bf16 v[162:165], v[82:85], v[130:133], v[162:165]
	v_mfma_f32_16x16x32_bf16 v[138:141], v[82:85], v[154:157], v[138:141]
	v_mfma_f32_16x16x32_bf16 v[134:137], v[106:109], v[154:157], v[134:137]
	v_mfma_f32_16x16x32_bf16 v[114:117], v[82:85], v[174:177], v[114:117]
	v_mfma_f32_16x16x32_bf16 v[110:113], v[106:109], v[174:177], v[110:113]
	v_mfma_f32_16x16x32_bf16 v[90:93], v[82:85], v[186:189], v[90:93]
	v_mfma_f32_16x16x32_bf16 v[86:89], v[106:109], v[186:189], v[86:89]
	v_mfma_f32_16x16x32_bf16 v[162:165], v[94:97], v[142:145], v[162:165]
	v_mfma_f32_16x16x32_bf16 v[130:133], v[106:109], v[130:133], v[158:161]
	v_mfma_f32_16x16x32_bf16 v[138:141], v[94:97], v[166:169], v[138:141]
	v_mfma_f32_16x16x32_bf16 v[134:137], v[118:121], v[166:169], v[134:137]
	v_mfma_f32_16x16x32_bf16 v[114:117], v[94:97], v[182:185], v[114:117]
	v_mfma_f32_16x16x32_bf16 v[110:113], v[118:121], v[182:185], v[110:113]
	v_mfma_f32_16x16x32_bf16 v[90:93], v[94:97], v[190:193], v[90:93]
	v_mfma_f32_16x16x32_bf16 v[86:89], v[118:121], v[190:193], v[86:89]
	v_mfma_f32_16x16x32_bf16 v[130:133], v[118:121], v[142:145], v[130:133]
	s_barrier
	s_setprio 0
	s_mov_b32 m0, s92
	ds_read_b128 v[142:145], v217 offset:16384
	ds_read_b128 v[154:157], v217 offset:17408
	ds_read_b128 v[158:161], v217 offset:18432
	ds_read_b128 v[166:169], v217 offset:19456
	ds_read_b128 v[174:177], v217 offset:20480
	ds_read_b128 v[182:185], v217 offset:21504
	ds_read_b128 v[186:189], v217 offset:22528
	ds_read_b128 v[190:193], v217 offset:23552
	buffer_load_dwordx4 v199, s[12:15], s58 offen lds
	s_mov_b32 m0, s93
	s_add_i32 s61, s58, 0x20000
	buffer_load_dwordx4 v215, s[12:15], s58 offen lds
	s_mov_b32 m0, s94
	s_nop 0
	buffer_load_dwordx4 v199, s[12:15], s61 offen lds
	s_mov_b32 m0, s95
	s_nop 0
	buffer_load_dwordx4 v215, s[12:15], s61 offen lds
	s_mov_b32 m0, s44
	s_nop 0
	buffer_load_dwordx4 v0, s[16:19], s60 offen lds
	s_mov_b32 m0, s36
	s_nop 0
	buffer_load_dwordx4 v214, s[16:19], s60 offen lds
	s_waitcnt vmcnt(8)
	s_waitcnt lgkmcnt(0)
	s_setprio 1
	s_barrier
	v_mfma_f32_16x16x32_bf16 v[78:81], v[34:37], v[142:145], v[78:81]
	v_mfma_f32_16x16x32_bf16 v[74:77], v[58:61], v[142:145], v[74:77]
	v_mfma_f32_16x16x32_bf16 v[54:57], v[34:37], v[158:161], v[54:57]
	v_mfma_f32_16x16x32_bf16 v[50:53], v[58:61], v[158:161], v[50:53]
	v_mfma_f32_16x16x32_bf16 v[30:33], v[34:37], v[174:177], v[30:33]
	v_mfma_f32_16x16x32_bf16 v[26:29], v[58:61], v[174:177], v[26:29]
	v_mfma_f32_16x16x32_bf16 v[14:17], v[34:37], v[186:189], v[14:17]
	v_mfma_f32_16x16x32_bf16 v[10:13], v[58:61], v[186:189], v[10:13]
	v_mfma_f32_16x16x32_bf16 v[78:81], v[46:49], v[154:157], v[78:81]
	v_mfma_f32_16x16x32_bf16 v[74:77], v[70:73], v[154:157], v[74:77]
	v_mfma_f32_16x16x32_bf16 v[54:57], v[46:49], v[166:169], v[54:57]
	v_mfma_f32_16x16x32_bf16 v[50:53], v[70:73], v[166:169], v[50:53]
	v_mfma_f32_16x16x32_bf16 v[30:33], v[46:49], v[182:185], v[30:33]
	v_mfma_f32_16x16x32_bf16 v[26:29], v[70:73], v[182:185], v[26:29]
	v_mfma_f32_16x16x32_bf16 v[14:17], v[46:49], v[190:193], v[14:17]
	v_mfma_f32_16x16x32_bf16 v[10:13], v[70:73], v[190:193], v[10:13]
	v_mfma_f32_16x16x32_bf16 v[42:45], v[82:85], v[158:161], v[42:45]
	v_mfma_f32_16x16x32_bf16 v[38:41], v[106:109], v[158:161], v[38:41]
	v_mfma_f32_16x16x32_bf16 v[22:25], v[82:85], v[174:177], v[22:25]
	v_mfma_f32_16x16x32_bf16 v[18:21], v[106:109], v[174:177], v[18:21]
	v_mfma_f32_16x16x32_bf16 v[6:9], v[82:85], v[186:189], v[6:9]
	v_mfma_f32_16x16x32_bf16 v[2:5], v[106:109], v[186:189], v[2:5]
	v_mfma_f32_16x16x32_bf16 v[34:37], v[82:85], v[142:145], v[66:69]
	v_mfma_f32_16x16x32_bf16 v[46:49], v[106:109], v[142:145], v[62:65]
	v_mfma_f32_16x16x32_bf16 v[42:45], v[94:97], v[166:169], v[42:45]
	v_mfma_f32_16x16x32_bf16 v[38:41], v[118:121], v[166:169], v[38:41]
	v_mfma_f32_16x16x32_bf16 v[22:25], v[94:97], v[182:185], v[22:25]
	v_mfma_f32_16x16x32_bf16 v[18:21], v[118:121], v[182:185], v[18:21]
	v_mfma_f32_16x16x32_bf16 v[6:9], v[94:97], v[190:193], v[6:9]
	v_mfma_f32_16x16x32_bf16 v[2:5], v[118:121], v[190:193], v[2:5]
	v_mfma_f32_16x16x32_bf16 v[34:37], v[94:97], v[154:157], v[34:37]
	v_mfma_f32_16x16x32_bf16 v[46:49], v[118:121], v[154:157], v[46:49]
	s_barrier
	s_setprio 0
	v_add_u32_e32 v70, 0x18000, v216
	v_add_u32_e32 v118, 0x1c000, v216
	ds_read_b128 v[58:61], v70
	ds_read_b128 v[62:65], v70 offset:1024
	ds_read_b128 v[66:69], v70 offset:2048
	ds_read_b128 v[70:73], v70 offset:3072
	ds_read_b128 v[82:85], v118
	ds_read_b128 v[94:97], v118 offset:1024
	ds_read_b128 v[106:109], v118 offset:2048
	ds_read_b128 v[118:121], v118 offset:3072
	s_add_i32 s60, s60, 0x20000
	s_mov_b32 m0, s37
	ds_read_b128 v[142:145], v217 offset:32768
	ds_read_b128 v[154:157], v217 offset:33792
	ds_read_b128 v[166:169], v217 offset:34816
	ds_read_b128 v[174:177], v217 offset:35840
	ds_read_b128 v[182:185], v217 offset:36864
	ds_read_b128 v[186:189], v217 offset:37888
	ds_read_b128 v[190:193], v217 offset:38912
	ds_read_b128 v[194:197], v217 offset:39936
	buffer_load_dwordx4 v0, s[16:19], s60 offen lds
	s_mov_b32 m0, s38
	s_nop 0
	buffer_load_dwordx4 v214, s[16:19], s60 offen lds
	s_waitcnt vmcnt(8)
	s_waitcnt lgkmcnt(0)
	s_nop 0
	s_setprio 1
	s_barrier
	v_mfma_f32_16x16x32_bf16 v[158:161], v[58:61], v[142:145], v[178:181]
	v_mfma_f32_16x16x32_bf16 v[178:181], v[62:65], v[154:157], v[158:161]
	v_mfma_f32_16x16x32_bf16 v[158:161], v[66:69], v[142:145], v[170:173]
	v_mfma_f32_16x16x32_bf16 v[150:153], v[58:61], v[166:169], v[150:153]
	v_mfma_f32_16x16x32_bf16 v[146:149], v[66:69], v[166:169], v[146:149]
	v_mfma_f32_16x16x32_bf16 v[126:129], v[58:61], v[182:185], v[126:129]
	v_mfma_f32_16x16x32_bf16 v[122:125], v[66:69], v[182:185], v[122:125]
	v_mfma_f32_16x16x32_bf16 v[102:105], v[58:61], v[190:193], v[102:105]
	v_mfma_f32_16x16x32_bf16 v[98:101], v[66:69], v[190:193], v[98:101]
	v_mfma_f32_16x16x32_bf16 v[170:173], v[70:73], v[154:157], v[158:161]
	v_mfma_f32_16x16x32_bf16 v[150:153], v[62:65], v[174:177], v[150:153]
	v_mfma_f32_16x16x32_bf16 v[146:149], v[70:73], v[174:177], v[146:149]
	v_mfma_f32_16x16x32_bf16 v[126:129], v[62:65], v[186:189], v[126:129]
	v_mfma_f32_16x16x32_bf16 v[122:125], v[70:73], v[186:189], v[122:125]
	v_mfma_f32_16x16x32_bf16 v[102:105], v[62:65], v[194:197], v[102:105]
	v_mfma_f32_16x16x32_bf16 v[98:101], v[70:73], v[194:197], v[98:101]
	v_mfma_f32_16x16x32_bf16 v[158:161], v[82:85], v[142:145], v[162:165]
	v_mfma_f32_16x16x32_bf16 v[130:133], v[106:109], v[142:145], v[130:133]
	v_mfma_f32_16x16x32_bf16 v[162:165], v[94:97], v[154:157], v[158:161]
	v_mfma_f32_16x16x32_bf16 v[158:161], v[118:121], v[154:157], v[130:133]
	v_mfma_f32_16x16x32_bf16 v[130:133], v[82:85], v[166:169], v[138:141]
	v_mfma_f32_16x16x32_bf16 v[138:141], v[94:97], v[174:177], v[130:133]
	v_mfma_f32_16x16x32_bf16 v[130:133], v[106:109], v[166:169], v[134:137]
	v_mfma_f32_16x16x32_bf16 v[114:117], v[82:85], v[182:185], v[114:117]
	v_mfma_f32_16x16x32_bf16 v[110:113], v[106:109], v[182:185], v[110:113]
	v_mfma_f32_16x16x32_bf16 v[90:93], v[82:85], v[190:193], v[90:93]
	v_mfma_f32_16x16x32_bf16 v[86:89], v[106:109], v[190:193], v[86:89]
	v_mfma_f32_16x16x32_bf16 v[134:137], v[118:121], v[174:177], v[130:133]
	v_mfma_f32_16x16x32_bf16 v[114:117], v[94:97], v[186:189], v[114:117]
	v_mfma_f32_16x16x32_bf16 v[110:113], v[118:121], v[186:189], v[110:113]
	v_mfma_f32_16x16x32_bf16 v[90:93], v[94:97], v[194:197], v[90:93]
	v_mfma_f32_16x16x32_bf16 v[86:89], v[118:121], v[194:197], v[86:89]
	s_barrier
	s_setprio 0
	s_mov_b32 m0, s39
	s_or_b32 s60, s58, 0x80
	ds_read_b128 v[130:133], v217 offset:49152
	ds_read_b128 v[142:145], v217 offset:50176
	ds_read_b128 v[154:157], v217 offset:51200
	ds_read_b128 v[166:169], v217 offset:52224
	ds_read_b128 v[174:177], v217 offset:53248
	ds_read_b128 v[182:185], v217 offset:54272
	ds_read_b128 v[186:189], v217 offset:55296
	ds_read_b128 v[190:193], v217 offset:56320
	buffer_load_dwordx4 v199, s[12:15], s60 offen lds
	s_mov_b32 m0, s40
	s_add_i32 s58, s58, 0x20080
	buffer_load_dwordx4 v215, s[12:15], s60 offen lds
	s_mov_b32 m0, s43
	s_nop 0
	buffer_load_dwordx4 v199, s[12:15], s58 offen lds
	s_mov_b32 m0, s42
	s_nop 0
	buffer_load_dwordx4 v215, s[12:15], s58 offen lds
	s_mov_b32 m0, s41
	s_nop 0
	buffer_load_dwordx4 v0, s[16:19], s59 offen lds
	s_mov_b32 m0, s33
	s_nop 0
	buffer_load_dwordx4 v214, s[16:19], s59 offen lds
	s_waitcnt vmcnt(8)
	s_waitcnt lgkmcnt(0)
	s_setprio 1
	s_barrier
	v_mfma_f32_16x16x32_bf16 v[78:81], v[58:61], v[130:133], v[78:81]
	v_mfma_f32_16x16x32_bf16 v[74:77], v[66:69], v[130:133], v[74:77]
	v_mfma_f32_16x16x32_bf16 v[54:57], v[58:61], v[154:157], v[54:57]
	v_mfma_f32_16x16x32_bf16 v[50:53], v[66:69], v[154:157], v[50:53]
	v_mfma_f32_16x16x32_bf16 v[30:33], v[58:61], v[174:177], v[30:33]
	v_mfma_f32_16x16x32_bf16 v[26:29], v[66:69], v[174:177], v[26:29]
	v_mfma_f32_16x16x32_bf16 v[14:17], v[58:61], v[186:189], v[14:17]
	v_mfma_f32_16x16x32_bf16 v[10:13], v[66:69], v[186:189], v[10:13]
	v_mfma_f32_16x16x32_bf16 v[78:81], v[62:65], v[142:145], v[78:81]
	v_mfma_f32_16x16x32_bf16 v[74:77], v[70:73], v[142:145], v[74:77]
	v_mfma_f32_16x16x32_bf16 v[54:57], v[62:65], v[166:169], v[54:57]
	v_mfma_f32_16x16x32_bf16 v[50:53], v[70:73], v[166:169], v[50:53]
	v_mfma_f32_16x16x32_bf16 v[30:33], v[62:65], v[182:185], v[30:33]
	v_mfma_f32_16x16x32_bf16 v[26:29], v[70:73], v[182:185], v[26:29]
	v_mfma_f32_16x16x32_bf16 v[14:17], v[62:65], v[190:193], v[14:17]
	v_mfma_f32_16x16x32_bf16 v[10:13], v[70:73], v[190:193], v[10:13]
	v_mfma_f32_16x16x32_bf16 v[34:37], v[82:85], v[130:133], v[34:37]
	v_mfma_f32_16x16x32_bf16 v[66:69], v[94:97], v[142:145], v[34:37]
	v_mfma_f32_16x16x32_bf16 v[34:37], v[106:109], v[130:133], v[46:49]
	v_mfma_f32_16x16x32_bf16 v[62:65], v[118:121], v[142:145], v[34:37]
	v_mfma_f32_16x16x32_bf16 v[34:37], v[82:85], v[154:157], v[42:45]
	v_mfma_f32_16x16x32_bf16 v[42:45], v[94:97], v[166:169], v[34:37]
	v_mfma_f32_16x16x32_bf16 v[34:37], v[106:109], v[154:157], v[38:41]
	v_mfma_f32_16x16x32_bf16 v[22:25], v[82:85], v[174:177], v[22:25]
	v_mfma_f32_16x16x32_bf16 v[18:21], v[106:109], v[174:177], v[18:21]
	v_mfma_f32_16x16x32_bf16 v[6:9], v[82:85], v[186:189], v[6:9]
	v_mfma_f32_16x16x32_bf16 v[2:5], v[106:109], v[186:189], v[2:5]
	v_mfma_f32_16x16x32_bf16 v[38:41], v[118:121], v[166:169], v[34:37]
	v_mfma_f32_16x16x32_bf16 v[22:25], v[94:97], v[182:185], v[22:25]
	v_mfma_f32_16x16x32_bf16 v[18:21], v[118:121], v[182:185], v[18:21]
	v_mfma_f32_16x16x32_bf16 v[6:9], v[94:97], v[190:193], v[6:9]
	v_mfma_f32_16x16x32_bf16 v[2:5], v[118:121], v[190:193], v[2:5]
	s_barrier
	s_setprio 0
	s_add_i32 s57, s57, 2
	s_addk_i32 s55, 0x100
	s_addk_i32 s56, 0x100
	s_cmp_gt_u32 s57, 5
	s_cbranch_scc0 .LBB0_702
	v_readlane_b32 s8, v251, 45
	v_readlane_b32 s9, v251, 46
	s_and_b64 vcc, exec, s[8:9]
	s_cbranch_vccz .LBB0_705
	s_barrier
